# EpiResidNorm false: ln/scale/shift loads hoisted above the cross-WG exchange, bj=1 loads behind bj=0 compute, 4 partial-sum loads issued together
# speedup vs baseline: 1.0091x; 1.0091x over previous
;     __device__ __forceinline__ void operator()(const f32x4 (&acc)[2][2][4][2], const Unit& u, int wr, int wc, int fr, int fq) const {
;     ...
;         asm volatile("s_waitcnt lgkmcnt(0)" ::: "memory"); __builtin_amdgcn_s_barrier(); asm volatile("" ::: "memory");
;         if (tid < 256) {
;             const float part = (red[tid * 4 + 0] + red[tid * 4 + 1]) + (red[tid * 4 + 2] + red[tid * 4 + 3]);
;             __hip_atomic_store(ss + (unsigned)(u.pm * 4 + u.pn) * 256 + tid, part, __ATOMIC_RELAXED, __HIP_MEMORY_SCOPE_AGENT);
;         }
;         asm volatile("s_waitcnt vmcnt(0)" ::: "memory");
;         __builtin_amdgcn_s_barrier(); asm volatile("" ::: "memory");
;         if (tid == 0) {
;             (void)__hip_atomic_fetch_add(cnt + 16 * u.pm, 1u, __ATOMIC_RELAXED, __HIP_MEMORY_SCOPE_AGENT);
;             unsigned spins = 0;
;             while (__hip_atomic_load(cnt + 16 * u.pm, __ATOMIC_RELAXED, __HIP_MEMORY_SCOPE_AGENT) < target) { __builtin_amdgcn_s_sleep(1); if (++spins > (1u << 20)) break; }
;         }
;         __builtin_amdgcn_s_barrier(); asm volatile("" ::: "memory");
;         if (tid < 256) {
;             float tot = 0.f;
; #pragma unroll
;             for (int q = 0; q < 4; ++q) tot += __hip_atomic_load(ss + (unsigned)(u.pm * 4 + q) * 256 + tid, __ATOMIC_RELAXED, __HIP_MEMORY_SCOPE_AGENT);
;             rs[tid] = rsqrtf(tot * (1.0f / 1024.0f) + 1e-6f);
;         }
;         asm volatile("s_waitcnt lgkmcnt(0)" ::: "memory"); __builtin_amdgcn_s_barrier(); asm volatile("" ::: "memory");
;         const float* sh = FINAL ? ln : shp + b * 9216; const float* sc = FINAL ? ln : scp + b * 9216;
; #pragma unroll
;         for (int bj = 0; bj < 2; ++bj) {
;             const int col = col0 + bj * HALF;
;             const f32x4 l0 = *(const f32x4*)(ln + col), l1 = *(const f32x4*)(ln + col + 4), s0 = *(const f32x4*)(sh + col), s1 = *(const f32x4*)(sh + col + 4),
;                         c0 = *(const f32x4*)(sc + col), c1 = *(const f32x4*)(sc + col + 4);
.LBB0_583:
	s_or_b64 exec, exec, s[28:29]
	s_add_u32 s64, s96, s26
	s_addc_u32 s65, s97, s27
	s_add_u32 s66, s54, s26
	s_addc_u32 s67, s55, s27
	v_lshlrev_b64 v[248:249], 2, v[150:151]
	v_lshl_add_u64 v[242:243], s[12:13], 0, v[248:249]
	v_lshl_add_u64 v[244:245], s[66:67], 0, v[248:249]
	v_lshl_add_u64 v[246:247], s[64:65], 0, v[248:249]
	global_load_dwordx4 v[218:221], v[242:243], off offset:16
	global_load_dwordx4 v[222:225], v[242:243], off
	global_load_dwordx4 v[226:229], v[244:245], off
	global_load_dwordx4 v[230:233], v[244:245], off offset:16
	global_load_dwordx4 v[234:237], v[246:247], off
	global_load_dwordx4 v[238:241], v[246:247], off offset:16
	s_waitcnt lgkmcnt(0)
	s_barrier
	s_and_saveexec_b64 s[28:29], s[6:7]
	s_cbranch_execz .LBB0_585
	v_readlane_b32 s36, v254, 43
	v_readlane_b32 s37, v254, 44
	v_readlane_b32 s38, v254, 45
	v_readlane_b32 s39, v254, 46
	v_readlane_b32 s40, v254, 47
	v_readlane_b32 s41, v254, 48
	v_readlane_b32 s42, v254, 49
	v_readlane_b32 s43, v254, 50
	v_readlane_b32 s44, v254, 51
	v_readlane_b32 s45, v254, 52
	v_readlane_b32 s46, v254, 53
	v_readlane_b32 s47, v254, 54
	v_readlane_b32 s48, v254, 55
	v_readlane_b32 s49, v254, 56
	v_readlane_b32 s50, v254, 57
	v_readlane_b32 s51, v254, 58
	s_mov_b32 s25, s45
	v_writelane_b32 v254, s36, 43
	s_waitcnt lgkmcnt(0)
	ds_read_b128 v[0:3], v207
	s_lshl_b32 s30, s73, 10
	v_writelane_b32 v254, s37, 44
	v_writelane_b32 v254, s38, 45
	v_writelane_b32 v254, s39, 46
	v_writelane_b32 v254, s40, 47
	v_writelane_b32 v254, s41, 48
	v_writelane_b32 v254, s42, 49
	v_writelane_b32 v254, s43, 50
	v_writelane_b32 v254, s44, 51
	v_writelane_b32 v254, s45, 52
	v_writelane_b32 v254, s46, 53
	v_writelane_b32 v254, s47, 54
	v_writelane_b32 v254, s48, 55
	s_waitcnt lgkmcnt(0)
	v_mov_b32_e32 v4, v1
	v_mov_b32_e32 v5, v2
	v_mov_b32_e32 v1, v3
	v_writelane_b32 v254, s49, 56
	s_add_i32 s24, s30, s24
	v_pk_add_f32 v[0:1], v[4:5], v[0:1]
	v_writelane_b32 v254, s50, 57
	v_pk_add_f32 v[0:1], v[0:1], v[0:1] op_sel:[0,1] op_sel_hi:[1,0]
	v_writelane_b32 v254, s51, 58
	v_lshl_add_u64 v[2:3], s[24:25], 2, v[140:141]
	global_store_dword v[2:3], v0, off sc1

;     __device__ __forceinline__ void operator()(const f32x4 (&acc)[2][2][4][2], const Unit& u, int wr, int wc, int fr, int fq) const {
;     ...
;         if (tid < 256) {
;             float tot = 0.f;
; #pragma unroll
;             for (int q = 0; q < 4; ++q) tot += __hip_atomic_load(ss + (unsigned)(u.pm * 4 + q) * 256 + tid, __ATOMIC_RELAXED, __HIP_MEMORY_SCOPE_AGENT);
;             rs[tid] = rsqrtf(tot * (1.0f / 1024.0f) + 1e-6f);
;         }
;         asm volatile("s_waitcnt lgkmcnt(0)" ::: "memory"); __builtin_amdgcn_s_barrier(); asm volatile("" ::: "memory");
;         const float* sh = FINAL ? ln : shp + b * 9216; const float* sc = FINAL ? ln : scp + b * 9216;
; #pragma unroll
;         for (int bj = 0; bj < 2; ++bj) {
;             const int col = col0 + bj * HALF;
;             const f32x4 l0 = *(const f32x4*)(ln + col), l1 = *(const f32x4*)(ln + col + 4), s0 = *(const f32x4*)(sh + col), s1 = *(const f32x4*)(sh + col + 4),
;                         c0 = *(const f32x4*)(sc + col), c1 = *(const f32x4*)(sc + col + 4);
; #pragma unroll
;             for (int ai = 0; ai < 2; ++ai)
; #pragma unroll
;                 for (int m = 0; m < 4; ++m) {
;                     const float rstd = rs[ai * HALF + wr * 64 + m * 16 + fr];
;                     const h16x8 o = ov[ai][m][bj];
;                     if (FINAL) {
;                         f32x4 y0, y1;
; #pragma unroll
;                         for (int j = 0; j < 4; ++j) { y0[j] = (float)o[j] * rstd * l0[j]; y1[j] = (float)o[4 + j] * rstd * l1[j]; }
;                         float* yp = fout + (unsigned)(row0 + ai * HALF + m * 16) * DM + col;
;                         *(f32x4*)yp = y0; *(f32x4*)(yp + 4) = y1;
;                     } else {
;                         h16x8 y;
; #pragma unroll
;                         for (int j = 0; j < 4; ++j) { y[j] = (h16)((float)o[j] * rstd * l0[j] * (1.0f + c0[j]) + s0[j]); y[4 + j] = (h16)((float)o[4 + j] * rstd * l1[j] * (1.0f + c1[j]) + s1[j]); }
;                         *(h16x8*)(xn + (unsigned)(row0 + ai * HALF + m * 16) * DM + col) = y;
.LBB0_601:
	s_or_b64 exec, exec, s[28:29]
	s_barrier
	s_and_saveexec_b64 s[28:29], s[6:7]
	s_cbranch_execz .LBB0_603
	v_readlane_b32 s36, v254, 43
	v_readlane_b32 s45, v254, 52
	s_mov_b32 s25, s45
	s_lshl_b32 s24, s73, 10
	s_waitcnt lgkmcnt(0)
	v_lshl_add_u64 v[0:1], s[24:25], 2, v[140:141]
	global_load_dword v2, v[0:1], off sc1
	global_load_dword v3, v[0:1], off offset:1024 sc1
	global_load_dword v6, v[0:1], off offset:2048 sc1
	global_load_dword v7, v[0:1], off offset:3072 sc1
	v_readlane_b32 s37, v254, 44
	v_readlane_b32 s38, v254, 45
	v_readlane_b32 s39, v254, 46
	v_readlane_b32 s40, v254, 47
	v_readlane_b32 s41, v254, 48
	v_readlane_b32 s42, v254, 49
	v_readlane_b32 s43, v254, 50
	v_readlane_b32 s44, v254, 51
	v_readlane_b32 s46, v254, 53
	v_readlane_b32 s47, v254, 54
	v_readlane_b32 s48, v254, 55
	v_readlane_b32 s49, v254, 56
	v_readlane_b32 s50, v254, 57
	v_readlane_b32 s51, v254, 58
	v_writelane_b32 v254, s36, 43
	s_mov_b32 s24, 0x800000
	s_waitcnt lgkmcnt(0)
	s_nop 0
	s_nop 0
	s_nop 0
	v_writelane_b32 v254, s37, 44
	s_nop 0
	v_writelane_b32 v254, s38, 45
	v_writelane_b32 v254, s39, 46
	v_writelane_b32 v254, s40, 47
	v_writelane_b32 v254, s41, 48
	v_writelane_b32 v254, s42, 49
	v_writelane_b32 v254, s43, 50
	v_writelane_b32 v254, s44, 51
	v_writelane_b32 v254, s45, 52
	v_writelane_b32 v254, s46, 53
	v_writelane_b32 v254, s47, 54
	v_writelane_b32 v254, s48, 55
	v_writelane_b32 v254, s49, 56
	v_writelane_b32 v254, s50, 57
	v_writelane_b32 v254, s51, 58
	s_waitcnt vmcnt(0) lgkmcnt(0)
	v_add_f32_e32 v2, 0, v2
	v_add_f32_e32 v2, v2, v3
	v_add_f32_e32 v2, v2, v6
	v_add_f32_e32 v0, v2, v7
	v_fmamk_f32 v0, v0, 0x3a800000, v193
	v_cmp_gt_f32_e32 vcc, s24, v0
	v_mul_f32_e32 v1, 0x4b800000, v0
	s_nop 0
	v_cndmask_b32_e32 v0, v0, v1, vcc
	v_rsq_f32_e32 v0, v0
	s_nop 0
	v_mul_f32_e32 v1, 0x45800000, v0
	v_cndmask_b32_e32 v0, v0, v1, vcc
	ds_write_b32 v204, v0
.LBB0_603:
	s_or_b64 exec, exec, s[28:29]
	s_add_u32 s28, s96, s26
	s_addc_u32 s29, s97, s27
	s_add_u32 s26, s54, s26
	v_lshlrev_b64 v[8:9], 2, v[150:151]
	s_addc_u32 s27, s55, s27
	s_waitcnt lgkmcnt(0)
	s_barrier
	v_lshl_add_u64 v[168:169], s[12:13], 0, v[8:9]
	v_lshl_add_u64 v[170:171], s[26:27], 0, v[8:9]
	s_waitcnt lgkmcnt(0)
	v_lshl_add_u64 v[172:173], s[28:29], 0, v[8:9]
	v_mov_b64_e32 v[0:1], v[218:219]
	v_mov_b64_e32 v[2:3], v[220:221]
	v_mov_b64_e32 v[4:5], v[222:223]
	v_mov_b64_e32 v[6:7], v[224:225]
	v_mov_b64_e32 v[208:209], v[226:227]
	v_mov_b64_e32 v[210:211], v[228:229]
	v_mov_b64_e32 v[212:213], v[230:231]
	v_mov_b64_e32 v[214:215], v[232:233]
	v_mov_b64_e32 v[12:13], v[234:235]
	v_mov_b64_e32 v[14:15], v[236:237]
	v_mov_b64_e32 v[8:9], v[238:239]
	v_mov_b64_e32 v[10:11], v[240:241]
	global_load_dwordx4 v[218:221], v[168:169], off offset:512
	global_load_dwordx4 v[222:225], v[170:171], off offset:512
	global_load_dwordx4 v[226:229], v[168:169], off offset:528
	global_load_dwordx4 v[230:233], v[170:171], off offset:528
	global_load_dwordx4 v[234:237], v[172:173], off offset:512
	global_load_dwordx4 v[238:241], v[172:173], off offset:528
	ds_read_b32 v32, v205
	v_mov_b32_e32 v149, v33
	v_lshlrev_b64 v[174:175], 1, v[150:151]
	v_lshl_add_u64 v[150:151], v[148:149], 1, s[84:85]
	v_lshl_add_u64 v[150:151], v[150:151], 0, v[174:175]
	s_waitcnt lgkmcnt(0)
	v_pk_mul_f32 v[124:125], v[32:33], v[124:125] op_sel_hi:[0,1]
	v_pk_mul_f32 v[128:129], v[32:33], v[128:129] op_sel_hi:[0,1]
	v_pk_mul_f32 v[122:123], v[32:33], v[122:123] op_sel_hi:[0,1]
	v_pk_mul_f32 v[126:127], v[32:33], v[126:127] op_sel_hi:[0,1]
	v_or_b32_e32 v32, 0x4000, v148
	s_and_b64 vcc, exec, s[10:11]
	s_mov_b64 s[10:11], -1
	s_nop 0
	v_pk_mul_f32 v[198:199], v[0:1], v[128:129]
	v_pk_mul_f32 v[196:197], v[4:5], v[124:125]
	v_pk_mul_f32 v[122:123], v[6:7], v[122:123]
	v_pk_mul_f32 v[216:217], v[2:3], v[126:127]
	v_pk_add_f32 v[176:177], v[208:209], 1.0 op_sel_hi:[1,0]
	v_pk_add_f32 v[128:129], v[212:213], 1.0 op_sel_hi:[1,0]
	v_pk_add_f32 v[126:127], v[210:211], 1.0 op_sel_hi:[1,0]
	v_pk_add_f32 v[124:125], v[214:215], 1.0 op_sel_hi:[1,0]
	v_pk_fma_f32 v[196:197], v[176:177], v[196:197], v[12:13]
	v_pk_fma_f32 v[198:199], v[128:129], v[198:199], v[8:9]
	v_pk_fma_f32 v[122:123], v[126:127], v[122:123], v[14:15]
	v_pk_fma_f32 v[212:213], v[124:125], v[216:217], v[10:11]
	v_cvt_pk_f16_f32 v208, v196, v197
	v_cvt_pk_f16_f32 v210, v198, v199
	v_cvt_pk_f16_f32 v209, v122, v123
	v_cvt_pk_f16_f32 v211, v212, v213
	global_store_dwordx4 v[150:151], v[208:211], off
	ds_read_b32 v196, v205 offset:64
	v_lshl_add_u64 v[122:123], v[32:33], 1, s[84:85]
	v_lshl_add_u64 v[122:123], v[122:123], 0, v[174:175]
	v_or_b32_e32 v32, 0x8000, v148
	s_waitcnt lgkmcnt(0)
	v_pk_mul_f32 v[108:109], v[196:197], v[108:109] op_sel_hi:[0,1]
	v_pk_mul_f32 v[112:113], v[196:197], v[112:113] op_sel_hi:[0,1]
	v_pk_mul_f32 v[106:107], v[196:197], v[106:107] op_sel_hi:[0,1]
	v_pk_mul_f32 v[110:111], v[196:197], v[110:111] op_sel_hi:[0,1]
	v_pk_mul_f32 v[108:109], v[4:5], v[108:109]
	v_pk_mul_f32 v[112:113], v[0:1], v[112:113]
	v_pk_mul_f32 v[106:107], v[6:7], v[106:107]
	v_pk_mul_f32 v[110:111], v[2:3], v[110:111]
	v_pk_fma_f32 v[108:109], v[176:177], v[108:109], v[12:13]
	v_pk_fma_f32 v[112:113], v[128:129], v[112:113], v[8:9]
	v_pk_fma_f32 v[196:197], v[126:127], v[106:107], v[14:15]
	v_pk_fma_f32 v[110:111], v[124:125], v[110:111], v[10:11]
	v_cvt_pk_f16_f32 v106, v108, v109
	v_cvt_pk_f16_f32 v108, v112, v113
	v_cvt_pk_f16_f32 v107, v196, v197
	v_cvt_pk_f16_f32 v109, v110, v111
	global_store_dwordx4 v[122:123], v[106:109], off
	ds_read_b32 v108, v205 offset:128
	s_waitcnt lgkmcnt(0)
;     __device__ __forceinline__ void operator()(const f32x4 (&acc)[2][2][4][2], const Unit& u, int wr, int wc, int fr, int fq) const {
;     ...
; #pragma unroll
;             for (int ai = 0; ai < 2; ++ai)
; #pragma unroll
;                 for (int m = 0; m < 4; ++m) {
;                     const float rstd = rs[ai * HALF + wr * 64 + m * 16 + fr];
;                     const h16x8 o = ov[ai][m][bj];
;                     if (FINAL) {
;                         f32x4 y0, y1;
; #pragma unroll
;                         for (int j = 0; j < 4; ++j) { y0[j] = (float)o[j] * rstd * l0[j]; y1[j] = (float)o[4 + j] * rstd * l1[j]; }
;                         float* yp = fout + (unsigned)(row0 + ai * HALF + m * 16) * DM + col;
;                         *(f32x4*)yp = y0; *(f32x4*)(yp + 4) = y1;
;                     } else {
;                         h16x8 y;
; #pragma unroll
;                         for (int j = 0; j < 4; ++j) { y[j] = (h16)((float)o[j] * rstd * l0[j] * (1.0f + c0[j]) + s0[j]); y[4 + j] = (h16)((float)o[4 + j] * rstd * l1[j] * (1.0f + c1[j]) + s1[j]); }
;                         *(h16x8*)(xn + (unsigned)(row0 + ai * HALF + m * 16) * DM + col) = y;
	v_pk_mul_f32 v[92:93], v[108:109], v[92:93] op_sel_hi:[0,1]
	v_pk_mul_f32 v[96:97], v[108:109], v[96:97] op_sel_hi:[0,1]
	v_pk_mul_f32 v[90:91], v[108:109], v[90:91] op_sel_hi:[0,1]
	v_pk_mul_f32 v[94:95], v[108:109], v[94:95] op_sel_hi:[0,1]
	v_pk_mul_f32 v[92:93], v[4:5], v[92:93]
	v_pk_mul_f32 v[96:97], v[0:1], v[96:97]
	v_pk_mul_f32 v[90:91], v[6:7], v[90:91]
	v_pk_mul_f32 v[94:95], v[2:3], v[94:95]
	v_lshl_add_u64 v[106:107], v[32:33], 1, s[84:85]
	v_pk_fma_f32 v[92:93], v[176:177], v[92:93], v[12:13]
	v_pk_fma_f32 v[96:97], v[128:129], v[96:97], v[8:9]
	v_pk_fma_f32 v[108:109], v[126:127], v[90:91], v[14:15]
	v_pk_fma_f32 v[94:95], v[124:125], v[94:95], v[10:11]
	v_lshl_add_u64 v[106:107], v[106:107], 0, v[174:175]
	v_cvt_pk_f16_f32 v90, v92, v93
	v_cvt_pk_f16_f32 v92, v96, v97
	v_cvt_pk_f16_f32 v91, v108, v109
	v_cvt_pk_f16_f32 v93, v94, v95
	global_store_dwordx4 v[106:107], v[90:93], off
	ds_read_b32 v92, v205 offset:192
	v_or_b32_e32 v32, 0xc000, v148
	v_lshl_add_u64 v[90:91], v[32:33], 1, s[84:85]
	v_lshl_add_u64 v[90:91], v[90:91], 0, v[174:175]
	v_add_u32_e32 v32, 0x20000, v148
	s_waitcnt lgkmcnt(0)
	v_pk_mul_f32 v[76:77], v[92:93], v[76:77] op_sel_hi:[0,1]
	v_pk_mul_f32 v[80:81], v[92:93], v[80:81] op_sel_hi:[0,1]
	v_pk_mul_f32 v[74:75], v[92:93], v[74:75] op_sel_hi:[0,1]
	v_pk_mul_f32 v[78:79], v[92:93], v[78:79] op_sel_hi:[0,1]
	v_pk_mul_f32 v[76:77], v[4:5], v[76:77]
	v_pk_mul_f32 v[80:81], v[0:1], v[80:81]
	v_pk_mul_f32 v[74:75], v[6:7], v[74:75]
	v_pk_mul_f32 v[78:79], v[2:3], v[78:79]
	v_pk_fma_f32 v[76:77], v[176:177], v[76:77], v[12:13]
	v_pk_fma_f32 v[80:81], v[128:129], v[80:81], v[8:9]
	v_pk_fma_f32 v[92:93], v[126:127], v[74:75], v[14:15]
	v_pk_fma_f32 v[78:79], v[124:125], v[78:79], v[10:11]
	v_cvt_pk_f16_f32 v74, v76, v77
	v_cvt_pk_f16_f32 v76, v80, v81
	v_cvt_pk_f16_f32 v75, v92, v93
	v_cvt_pk_f16_f32 v77, v78, v79
	global_store_dwordx4 v[90:91], v[74:77], off
	ds_read_b32 v76, v205 offset:512
	s_waitcnt lgkmcnt(0)
	v_pk_mul_f32 v[60:61], v[76:77], v[60:61] op_sel_hi:[0,1]
	v_pk_mul_f32 v[64:65], v[76:77], v[64:65] op_sel_hi:[0,1]
	v_pk_mul_f32 v[58:59], v[76:77], v[58:59] op_sel_hi:[0,1]
	v_pk_mul_f32 v[62:63], v[76:77], v[62:63] op_sel_hi:[0,1]
	v_pk_mul_f32 v[60:61], v[4:5], v[60:61]
	v_pk_mul_f32 v[64:65], v[0:1], v[64:65]
	v_pk_mul_f32 v[58:59], v[6:7], v[58:59]
	v_pk_mul_f32 v[62:63], v[2:3], v[62:63]
	v_lshl_add_u64 v[74:75], v[32:33], 1, s[84:85]
	v_pk_fma_f32 v[60:61], v[176:177], v[60:61], v[12:13]
	v_pk_fma_f32 v[64:65], v[128:129], v[64:65], v[8:9]
	v_pk_fma_f32 v[76:77], v[126:127], v[58:59], v[14:15]
	v_pk_fma_f32 v[62:63], v[124:125], v[62:63], v[10:11]
	v_lshl_add_u64 v[74:75], v[74:75], 0, v[174:175]
	v_cvt_pk_f16_f32 v58, v60, v61
	v_cvt_pk_f16_f32 v60, v64, v65
	v_cvt_pk_f16_f32 v59, v76, v77
	v_cvt_pk_f16_f32 v61, v62, v63
	global_store_dwordx4 v[74:75], v[58:61], off
	ds_read_b32 v32, v205 offset:576
	s_waitcnt lgkmcnt(0)
	v_pk_mul_f32 v[46:47], v[32:33], v[46:47] op_sel_hi:[0,1]
	v_pk_mul_f32 v[42:43], v[32:33], v[42:43] op_sel_hi:[0,1]
	v_pk_mul_f32 v[48:49], v[32:33], v[48:49] op_sel_hi:[0,1]
	v_pk_mul_f32 v[44:45], v[32:33], v[44:45] op_sel_hi:[0,1]
	v_pk_mul_f32 v[46:47], v[0:1], v[46:47]
	v_pk_mul_f32 v[42:43], v[2:3], v[42:43]
	v_pk_mul_f32 v[48:49], v[4:5], v[48:49]
	v_pk_mul_f32 v[58:59], v[6:7], v[44:45]
	v_pk_fma_f32 v[46:47], v[128:129], v[46:47], v[8:9]
	v_pk_fma_f32 v[42:43], v[124:125], v[42:43], v[10:11]
	v_add_u32_e32 v32, 0x24000, v148
	v_pk_fma_f32 v[44:45], v[176:177], v[48:49], v[12:13]
	v_cvt_pk_f16_f32 v46, v46, v47
	v_pk_fma_f32 v[48:49], v[126:127], v[58:59], v[14:15]
	v_cvt_pk_f16_f32 v47, v42, v43
	v_lshl_add_u64 v[42:43], v[32:33], 1, s[84:85]
	v_cvt_pk_f16_f32 v44, v44, v45
	v_cvt_pk_f16_f32 v45, v48, v49
	v_lshl_add_u64 v[42:43], v[42:43], 0, v[174:175]
	global_store_dwordx4 v[42:43], v[44:47], off
	ds_read_b32 v32, v205 offset:640
	s_waitcnt lgkmcnt(0)
	v_pk_mul_f32 v[24:25], v[32:33], v[24:25] op_sel_hi:[0,1]
	v_pk_mul_f32 v[30:31], v[32:33], v[30:31] op_sel_hi:[0,1]
	v_pk_mul_f32 v[28:29], v[32:33], v[28:29] op_sel_hi:[0,1]
	v_pk_mul_f32 v[26:27], v[32:33], v[26:27] op_sel_hi:[0,1]
	v_pk_mul_f32 v[24:25], v[2:3], v[24:25]
	v_pk_mul_f32 v[30:31], v[4:5], v[30:31]
	v_pk_mul_f32 v[28:29], v[0:1], v[28:29]
	v_pk_mul_f32 v[26:27], v[6:7], v[26:27]
	v_pk_fma_f32 v[24:25], v[124:125], v[24:25], v[10:11]
	v_add_u32_e32 v32, 0x28000, v148
	v_pk_fma_f32 v[30:31], v[176:177], v[30:31], v[12:13]
	v_pk_fma_f32 v[28:29], v[128:129], v[28:29], v[8:9]
	v_pk_fma_f32 v[26:27], v[126:127], v[26:27], v[14:15]
	v_cvt_pk_f16_f32 v47, v24, v25
	v_lshl_add_u64 v[24:25], v[32:33], 1, s[84:85]
	v_cvt_pk_f16_f32 v44, v30, v31
	v_cvt_pk_f16_f32 v46, v28, v29
	v_cvt_pk_f16_f32 v45, v26, v27
	v_lshl_add_u64 v[24:25], v[24:25], 0, v[174:175]
	global_store_dwordx4 v[24:25], v[44:47], off
	ds_read_b32 v30, v205 offset:704
	v_add_u32_e32 v32, 0x2c000, v148
	s_waitcnt lgkmcnt(0)
	v_pk_mul_f32 v[26:27], v[30:31], v[166:167] op_sel_hi:[0,1]
	v_pk_mul_f32 v[4:5], v[4:5], v[26:27]
	s_nop 0
	v_pk_fma_f32 v[4:5], v[176:177], v[4:5], v[12:13]
	s_nop 0
	v_cvt_pk_f16_f32 v26, v4, v5
	v_pk_mul_f32 v[4:5], v[30:31], v[162:163] op_sel_hi:[0,1]
	v_pk_mul_f32 v[0:1], v[0:1], v[4:5]
	s_nop 0
	v_pk_fma_f32 v[0:1], v[128:129], v[0:1], v[8:9]
	s_nop 0
	v_cvt_pk_f16_f32 v28, v0, v1
	v_pk_mul_f32 v[0:1], v[30:31], v[164:165] op_sel_hi:[0,1]
	v_pk_mul_f32 v[0:1], v[6:7], v[0:1]
	s_nop 0
	v_pk_fma_f32 v[0:1], v[126:127], v[0:1], v[14:15]
	s_nop 0
	v_cvt_pk_f16_f32 v27, v0, v1
	v_pk_mul_f32 v[0:1], v[30:31], v[160:161] op_sel_hi:[0,1]
	v_pk_mul_f32 v[0:1], v[2:3], v[0:1]
	s_nop 0
	v_pk_fma_f32 v[0:1], v[124:125], v[0:1], v[10:11]
	s_nop 0
	v_cvt_pk_f16_f32 v29, v0, v1
	v_lshl_add_u64 v[0:1], v[32:33], 1, s[84:85]
	v_lshl_add_u64 v[0:1], v[0:1], 0, v[174:175]
	global_store_dwordx4 v[0:1], v[26:29], off
	s_waitcnt vmcnt(8)
;     __device__ __forceinline__ void operator()(const f32x4 (&acc)[2][2][4][2], const Unit& u, int wr, int wc, int fr, int fq) const {
;     ...
;         const float* sh = FINAL ? ln : shp + b * 9216; const float* sc = FINAL ? ln : scp + b * 9216;
; #pragma unroll
;         for (int bj = 0; bj < 2; ++bj) {
;             const int col = col0 + bj * HALF;
;             const f32x4 l0 = *(const f32x4*)(ln + col), l1 = *(const f32x4*)(ln + col + 4), s0 = *(const f32x4*)(sh + col), s1 = *(const f32x4*)(sh + col + 4),
;                         c0 = *(const f32x4*)(sc + col), c1 = *(const f32x4*)(sc + col + 4);
; #pragma unroll
;             for (int ai = 0; ai < 2; ++ai)
; #pragma unroll
;                 for (int m = 0; m < 4; ++m) {
;                     const float rstd = rs[ai * HALF + wr * 64 + m * 16 + fr];
;                     const h16x8 o = ov[ai][m][bj];
;                     if (FINAL) {
;                         f32x4 y0, y1;
; #pragma unroll
;                         for (int j = 0; j < 4; ++j) { y0[j] = (float)o[j] * rstd * l0[j]; y1[j] = (float)o[4 + j] * rstd * l1[j]; }
;                         float* yp = fout + (unsigned)(row0 + ai * HALF + m * 16) * DM + col;
;                         *(f32x4*)yp = y0; *(f32x4*)(yp + 4) = y1;
;                     } else {
;                         h16x8 y;
; #pragma unroll
;                         for (int j = 0; j < 4; ++j) { y[j] = (h16)((float)o[j] * rstd * l0[j] * (1.0f + c0[j]) + s0[j]); y[4 + j] = (h16)((float)o[4 + j] * rstd * l1[j] * (1.0f + c1[j]) + s1[j]); }
;                         *(h16x8*)(xn + (unsigned)(row0 + ai * HALF + m * 16) * DM + col) = y;
	v_mov_b64_e32 v[2:3], v[218:219]
	v_mov_b64_e32 v[4:5], v[220:221]
	v_mov_b64_e32 v[6:7], v[222:223]
	v_mov_b64_e32 v[8:9], v[224:225]
	v_mov_b64_e32 v[10:11], v[226:227]
	v_mov_b64_e32 v[12:13], v[228:229]
	v_mov_b64_e32 v[44:45], v[234:235]
	v_mov_b64_e32 v[46:47], v[236:237]
	v_mov_b64_e32 v[58:59], v[238:239]
	v_mov_b64_e32 v[60:61], v[240:241]
	v_mov_b64_e32 v[26:27], v[230:231]
	v_mov_b64_e32 v[28:29], v[232:233]
	s_nop 0
	ds_read_b32 v14, v205
	s_waitcnt lgkmcnt(0)
	v_pk_mul_f32 v[30:31], v[14:15], v[120:121] op_sel_hi:[0,1]
	v_pk_mul_f32 v[48:49], v[14:15], v[118:119] op_sel_hi:[0,1]
	v_pk_mul_f32 v[62:63], v[14:15], v[116:117] op_sel_hi:[0,1]
	v_pk_mul_f32 v[14:15], v[14:15], v[114:115] op_sel_hi:[0,1]
	s_nop 0
	v_pk_mul_f32 v[30:31], v[2:3], v[30:31]
	v_pk_add_f32 v[64:65], v[6:7], 1.0 op_sel_hi:[1,0]
	v_pk_mul_f32 v[6:7], v[10:11], v[48:49]
	v_pk_add_f32 v[26:27], v[26:27], 1.0 op_sel_hi:[1,0]
	v_pk_mul_f32 v[48:49], v[4:5], v[62:63]
	v_pk_add_f32 v[62:63], v[8:9], 1.0 op_sel_hi:[1,0]
	v_pk_mul_f32 v[8:9], v[12:13], v[14:15]
	v_pk_add_f32 v[14:15], v[28:29], 1.0 op_sel_hi:[1,0]
	v_pk_fma_f32 v[28:29], v[64:65], v[30:31], v[44:45]
	v_pk_fma_f32 v[30:31], v[26:27], v[6:7], v[58:59]
	v_pk_fma_f32 v[48:49], v[62:63], v[48:49], v[46:47]
	v_pk_fma_f32 v[76:77], v[14:15], v[8:9], v[60:61]
	v_cvt_pk_f16_f32 v6, v28, v29
	v_cvt_pk_f16_f32 v8, v30, v31
	v_cvt_pk_f16_f32 v7, v48, v49
	v_cvt_pk_f16_f32 v9, v76, v77
	global_store_dwordx4 v[150:151], v[6:9], off offset:256
	ds_read_b32 v6, v205 offset:64
	s_waitcnt lgkmcnt(0)
	v_pk_mul_f32 v[28:29], v[6:7], v[102:103] op_sel_hi:[0,1]
	v_pk_mul_f32 v[8:9], v[6:7], v[104:105] op_sel_hi:[0,1]
	v_pk_mul_f32 v[30:31], v[6:7], v[100:101] op_sel_hi:[0,1]
	v_pk_mul_f32 v[6:7], v[6:7], v[98:99] op_sel_hi:[0,1]
	v_pk_mul_f32 v[8:9], v[2:3], v[8:9]
	v_pk_mul_f32 v[28:29], v[10:11], v[28:29]
	v_pk_mul_f32 v[30:31], v[4:5], v[30:31]
	v_pk_mul_f32 v[6:7], v[12:13], v[6:7]
	v_pk_fma_f32 v[8:9], v[64:65], v[8:9], v[44:45]
	v_pk_fma_f32 v[28:29], v[26:27], v[28:29], v[58:59]
	v_pk_fma_f32 v[30:31], v[62:63], v[30:31], v[46:47]
	v_pk_fma_f32 v[48:49], v[14:15], v[6:7], v[60:61]
	v_cvt_pk_f16_f32 v6, v8, v9
	v_cvt_pk_f16_f32 v8, v28, v29
	v_cvt_pk_f16_f32 v7, v30, v31
	v_cvt_pk_f16_f32 v9, v48, v49
	global_store_dwordx4 v[122:123], v[6:9], off offset:256
	ds_read_b32 v6, v205 offset:128
	s_waitcnt lgkmcnt(0)
	v_pk_mul_f32 v[28:29], v[6:7], v[86:87] op_sel_hi:[0,1]
	v_pk_mul_f32 v[8:9], v[6:7], v[88:89] op_sel_hi:[0,1]
	v_pk_mul_f32 v[30:31], v[6:7], v[84:85] op_sel_hi:[0,1]
	v_pk_mul_f32 v[6:7], v[6:7], v[82:83] op_sel_hi:[0,1]
	v_pk_mul_f32 v[8:9], v[2:3], v[8:9]
	v_pk_mul_f32 v[28:29], v[10:11], v[28:29]
	v_pk_mul_f32 v[30:31], v[4:5], v[30:31]
	v_pk_mul_f32 v[6:7], v[12:13], v[6:7]
	v_pk_fma_f32 v[8:9], v[64:65], v[8:9], v[44:45]
	v_pk_fma_f32 v[28:29], v[26:27], v[28:29], v[58:59]
	v_pk_fma_f32 v[30:31], v[62:63], v[30:31], v[46:47]
	v_pk_fma_f32 v[48:49], v[14:15], v[6:7], v[60:61]
	v_cvt_pk_f16_f32 v6, v8, v9
	v_cvt_pk_f16_f32 v8, v28, v29
	v_cvt_pk_f16_f32 v7, v30, v31
	v_cvt_pk_f16_f32 v9, v48, v49
	global_store_dwordx4 v[106:107], v[6:9], off offset:256
	ds_read_b32 v6, v205 offset:192
	s_waitcnt lgkmcnt(0)
	v_pk_mul_f32 v[28:29], v[6:7], v[70:71] op_sel_hi:[0,1]
	v_pk_mul_f32 v[8:9], v[6:7], v[72:73] op_sel_hi:[0,1]
	v_pk_mul_f32 v[30:31], v[6:7], v[68:69] op_sel_hi:[0,1]
	v_pk_mul_f32 v[6:7], v[6:7], v[66:67] op_sel_hi:[0,1]
	v_pk_mul_f32 v[8:9], v[2:3], v[8:9]
	v_pk_mul_f32 v[28:29], v[10:11], v[28:29]
	v_pk_mul_f32 v[30:31], v[4:5], v[30:31]
	v_pk_mul_f32 v[6:7], v[12:13], v[6:7]
	v_pk_fma_f32 v[8:9], v[64:65], v[8:9], v[44:45]
	v_pk_fma_f32 v[28:29], v[26:27], v[28:29], v[58:59]
	v_pk_fma_f32 v[30:31], v[62:63], v[30:31], v[46:47]
	v_pk_fma_f32 v[48:49], v[14:15], v[6:7], v[60:61]
	v_cvt_pk_f16_f32 v6, v8, v9
	v_cvt_pk_f16_f32 v8, v28, v29
	v_cvt_pk_f16_f32 v7, v30, v31
	v_cvt_pk_f16_f32 v9, v48, v49
	global_store_dwordx4 v[90:91], v[6:9], off offset:256
	ds_read_b32 v28, v205 offset:512
	s_waitcnt lgkmcnt(0)
; #define PG8_BAR __builtin_amdgcn_s_barrier()
;     __device__ __forceinline__ void operator()(const f32x4 (&acc)[2][2][4][2], const Unit& u, int wr, int wc, int fr, int fq) const {
;     ...
; #pragma unroll
;             for (int ai = 0; ai < 2; ++ai)
; #pragma unroll
;                 for (int m = 0; m < 4; ++m) {
;                     const float rstd = rs[ai * HALF + wr * 64 + m * 16 + fr];
;                     const h16x8 o = ov[ai][m][bj];
;                     if (FINAL) {
;                         f32x4 y0, y1;
; #pragma unroll
;                         for (int j = 0; j < 4; ++j) { y0[j] = (float)o[j] * rstd * l0[j]; y1[j] = (float)o[4 + j] * rstd * l1[j]; }
;                         float* yp = fout + (unsigned)(row0 + ai * HALF + m * 16) * DM + col;
;                         *(f32x4*)yp = y0; *(f32x4*)(yp + 4) = y1;
;                     } else {
;                         h16x8 y;
; #pragma unroll
;                         for (int j = 0; j < 4; ++j) { y[j] = (h16)((float)o[j] * rstd * l0[j] * (1.0f + c0[j]) + s0[j]); y[4 + j] = (h16)((float)o[4 + j] * rstd * l1[j] * (1.0f + c1[j]) + s1[j]); }
;                         *(h16x8*)(xn + (unsigned)(row0 + ai * HALF + m * 16) * DM + col) = y;
;                     }
;                 }
;         }
; template <class Epi>
; __device__ __forceinline__ void gemm_phase(LAS unsigned char* lds, const Gemm g, const StaticOrder& S, const Epi& E) {
;     ...
;         if (wr == 1) PG8_BAR;
	v_pk_mul_f32 v[30:31], v[28:29], v[52:53] op_sel_hi:[0,1]
	v_pk_mul_f32 v[6:7], v[28:29], v[56:57] op_sel_hi:[0,1]
	v_pk_mul_f32 v[8:9], v[28:29], v[54:55] op_sel_hi:[0,1]
	v_pk_mul_f32 v[28:29], v[28:29], v[50:51] op_sel_hi:[0,1]
	v_pk_mul_f32 v[6:7], v[2:3], v[6:7]
	v_pk_mul_f32 v[8:9], v[10:11], v[8:9]
	v_pk_mul_f32 v[30:31], v[4:5], v[30:31]
	v_pk_mul_f32 v[28:29], v[12:13], v[28:29]
	v_pk_fma_f32 v[6:7], v[64:65], v[6:7], v[44:45]
	v_pk_fma_f32 v[8:9], v[26:27], v[8:9], v[58:59]
	v_pk_fma_f32 v[30:31], v[62:63], v[30:31], v[46:47]
	v_pk_fma_f32 v[28:29], v[14:15], v[28:29], v[60:61]
	v_cvt_pk_f16_f32 v6, v6, v7
	v_cvt_pk_f16_f32 v8, v8, v9
	v_cvt_pk_f16_f32 v7, v30, v31
	v_cvt_pk_f16_f32 v9, v28, v29
	global_store_dwordx4 v[74:75], v[6:9], off offset:256
	ds_read_b32 v28, v205 offset:576
	s_waitcnt lgkmcnt(0)
	v_pk_mul_f32 v[30:31], v[28:29], v[36:37] op_sel_hi:[0,1]
	v_pk_mul_f32 v[6:7], v[28:29], v[40:41] op_sel_hi:[0,1]
	v_pk_mul_f32 v[8:9], v[28:29], v[38:39] op_sel_hi:[0,1]
	v_pk_mul_f32 v[28:29], v[28:29], v[34:35] op_sel_hi:[0,1]
	v_pk_mul_f32 v[6:7], v[2:3], v[6:7]
	v_pk_mul_f32 v[8:9], v[10:11], v[8:9]
	v_pk_mul_f32 v[30:31], v[4:5], v[30:31]
	v_pk_mul_f32 v[28:29], v[12:13], v[28:29]
	v_pk_fma_f32 v[6:7], v[64:65], v[6:7], v[44:45]
	v_pk_fma_f32 v[8:9], v[26:27], v[8:9], v[58:59]
	v_pk_fma_f32 v[30:31], v[62:63], v[30:31], v[46:47]
	v_pk_fma_f32 v[28:29], v[14:15], v[28:29], v[60:61]
	v_cvt_pk_f16_f32 v6, v6, v7
	v_cvt_pk_f16_f32 v8, v8, v9
	v_cvt_pk_f16_f32 v7, v30, v31
	v_cvt_pk_f16_f32 v9, v28, v29
	global_store_dwordx4 v[42:43], v[6:9], off offset:256
	ds_read_b32 v28, v205 offset:640
	s_waitcnt lgkmcnt(0)
	v_pk_mul_f32 v[18:19], v[28:29], v[18:19] op_sel_hi:[0,1]
	v_pk_mul_f32 v[6:7], v[28:29], v[22:23] op_sel_hi:[0,1]
	v_pk_mul_f32 v[8:9], v[28:29], v[20:21] op_sel_hi:[0,1]
	v_pk_mul_f32 v[16:17], v[28:29], v[16:17] op_sel_hi:[0,1]
	v_pk_mul_f32 v[6:7], v[2:3], v[6:7]
	v_pk_mul_f32 v[8:9], v[10:11], v[8:9]
	v_pk_mul_f32 v[18:19], v[4:5], v[18:19]
	v_pk_mul_f32 v[16:17], v[12:13], v[16:17]
	v_pk_fma_f32 v[6:7], v[64:65], v[6:7], v[44:45]
	v_pk_fma_f32 v[8:9], v[26:27], v[8:9], v[58:59]
	v_pk_fma_f32 v[18:19], v[62:63], v[18:19], v[46:47]
	v_pk_fma_f32 v[16:17], v[14:15], v[16:17], v[60:61]
	v_cvt_pk_f16_f32 v6, v6, v7
	v_cvt_pk_f16_f32 v8, v8, v9
	v_cvt_pk_f16_f32 v7, v18, v19
	v_cvt_pk_f16_f32 v9, v16, v17
	global_store_dwordx4 v[24:25], v[6:9], off offset:256
	ds_read_b32 v16, v205 offset:704
	s_waitcnt lgkmcnt(0)
	v_pk_mul_f32 v[6:7], v[16:17], v[158:159] op_sel_hi:[0,1]
	v_pk_mul_f32 v[2:3], v[2:3], v[6:7]
	s_nop 0
	v_pk_fma_f32 v[2:3], v[64:65], v[2:3], v[44:45]
	s_nop 0
	v_cvt_pk_f16_f32 v6, v2, v3
	v_pk_mul_f32 v[2:3], v[16:17], v[154:155] op_sel_hi:[0,1]
	v_pk_mul_f32 v[2:3], v[10:11], v[2:3]
	s_nop 0
	v_pk_fma_f32 v[2:3], v[26:27], v[2:3], v[58:59]
	s_nop 0
	v_cvt_pk_f16_f32 v8, v2, v3
	v_pk_mul_f32 v[2:3], v[16:17], v[156:157] op_sel_hi:[0,1]
	v_pk_mul_f32 v[2:3], v[4:5], v[2:3]
	s_nop 0
	v_pk_fma_f32 v[2:3], v[62:63], v[2:3], v[46:47]
	s_nop 0
	v_cvt_pk_f16_f32 v7, v2, v3
	v_pk_mul_f32 v[2:3], v[16:17], v[152:153] op_sel_hi:[0,1]
	v_pk_mul_f32 v[2:3], v[12:13], v[2:3]
	s_nop 0
	v_pk_fma_f32 v[2:3], v[14:15], v[2:3], v[60:61]
	s_nop 0
	v_cvt_pk_f16_f32 v9, v2, v3
	global_store_dwordx4 v[0:1], v[6:9], off offset:256
	s_cbranch_vccnz .LBB0_552
	s_andn2_b64 vcc, exec, s[62:63]
	s_cbranch_vccnz .LBB0_551
	s_barrier
	s_branch .LBB0_551
